# norm fusion: cached row scales keyed on the row block (recomputed if a workgroup's tile changes row block), otherwise identical to the previous best
# baseline (speedup 1.0000x reference)
.LBB0_189:
	s_add_u32 s1, s68, 0xfff80080
	s_addc_u32 s2, s69, -1
	s_add_i32 s3, 0, 0x10000
	v_add_u32_e32 v154, s3, v143
	ds_read_b128 v[138:141], v154
	ds_read_b128 v[146:149], v154 offset:1024
	ds_read_b128 v[150:153], v154 offset:2048
	ds_read_b128 v[154:157], v154 offset:3072
	s_cmp_eq_u32 s87, 28
	s_cselect_b32 s73, s43, s2
	s_cselect_b32 s72, s81, s1
	s_cselect_b32 s71, s41, s86
	s_cselect_b32 s70, s82, s83
	v_lshl_add_u64 v[174:175], s[68:69], 0, v[134:135]
	s_add_i32 m0, s60, 0xc000
	ds_read_b128 v[158:161], v145
	ds_read_b128 v[162:165], v145 offset:1024
	ds_read_b128 v[166:169], v145 offset:2048
	ds_read_b128 v[170:173], v145 offset:3072
	ds_read_b128 v[182:185], v145 offset:4096
	ds_read_b128 v[206:209], v145 offset:5120
	ds_read_b128 v[210:213], v145 offset:6144
	ds_read_b128 v[214:217], v145 offset:7168
	global_load_lds_dwordx4 v[174:175], off
	v_lshl_add_u64 v[174:175], s[68:69], 0, v[136:137]
	s_add_i32 m0, s60, 0xe000
	s_nop 0
	global_load_lds_dwordx4 v[174:175], off
	s_waitcnt lgkmcnt(8)
	s_barrier
	s_waitcnt lgkmcnt(0)
	s_setprio 1
	s_waitcnt lgkmcnt(0)
	v_mfma_f32_16x16x32_bf16 v[124:127], v[138:141], v[158:161], v[124:127]
	v_mfma_f32_16x16x32_bf16 v[120:123], v[150:153], v[158:161], v[120:123]
	v_mfma_f32_16x16x32_bf16 v[116:119], v[138:141], v[166:169], v[116:119]
	v_mfma_f32_16x16x32_bf16 v[108:111], v[150:153], v[166:169], v[108:111]
	v_mfma_f32_16x16x32_bf16 v[100:103], v[138:141], v[182:185], v[100:103]
	v_mfma_f32_16x16x32_bf16 v[92:95], v[150:153], v[182:185], v[92:95]
	v_mfma_f32_16x16x32_bf16 v[84:87], v[138:141], v[210:213], v[84:87]
	v_mfma_f32_16x16x32_bf16 v[76:79], v[150:153], v[210:213], v[76:79]
	v_mfma_f32_16x16x32_bf16 v[124:127], v[146:149], v[162:165], v[124:127]
	v_mfma_f32_16x16x32_bf16 v[120:123], v[154:157], v[162:165], v[120:123]
	v_mfma_f32_16x16x32_bf16 v[116:119], v[146:149], v[170:173], v[116:119]
	v_mfma_f32_16x16x32_bf16 v[108:111], v[154:157], v[170:173], v[108:111]
	v_mfma_f32_16x16x32_bf16 v[100:103], v[146:149], v[206:209], v[100:103]
	v_mfma_f32_16x16x32_bf16 v[92:95], v[154:157], v[206:209], v[92:95]
	v_mfma_f32_16x16x32_bf16 v[84:87], v[146:149], v[214:217], v[84:87]
	v_mfma_f32_16x16x32_bf16 v[76:79], v[154:157], v[214:217], v[76:79]
	s_setprio 0
	s_barrier
	s_add_i32 s1, 0, 0x14000
	v_add_u32_e32 v174, s1, v143
	s_add_i32 s2, s3, s53
	ds_read_b128 v[218:221], v174
	ds_read_b128 v[222:225], v174 offset:1024
	ds_read_b128 v[226:229], v174 offset:2048
	ds_read_b128 v[230:233], v174 offset:3072
	v_lshl_add_u64 v[174:175], s[70:71], 0, v[176:177]
	s_mov_b32 m0, s2
	v_lshl_add_u64 v[186:187], s[70:71], 0, v[128:129]
	global_load_lds_dwordx4 v[174:175], off
	s_add_i32 m0, s2, 0x2000
	s_nop 0
	global_load_lds_dwordx4 v[186:187], off
	s_barrier
	s_waitcnt lgkmcnt(0)
	s_setprio 1
	s_waitcnt lgkmcnt(0)
	v_mfma_f32_16x16x32_bf16 v[112:115], v[218:221], v[158:161], v[112:115]
	v_mfma_f32_16x16x32_bf16 v[104:107], v[226:229], v[158:161], v[104:107]
	v_mfma_f32_16x16x32_bf16 v[96:99], v[218:221], v[166:169], v[96:99]
	v_mfma_f32_16x16x32_bf16 v[88:91], v[226:229], v[166:169], v[88:91]
	v_mfma_f32_16x16x32_bf16 v[80:83], v[218:221], v[182:185], v[80:83]
	v_mfma_f32_16x16x32_bf16 v[72:75], v[226:229], v[182:185], v[72:75]
	v_mfma_f32_16x16x32_bf16 v[68:71], v[218:221], v[210:213], v[68:71]
	v_mfma_f32_16x16x32_bf16 v[64:67], v[226:229], v[210:213], v[64:67]
	v_mfma_f32_16x16x32_bf16 v[112:115], v[222:225], v[162:165], v[112:115]
	v_mfma_f32_16x16x32_bf16 v[104:107], v[230:233], v[162:165], v[104:107]
	v_mfma_f32_16x16x32_bf16 v[96:99], v[222:225], v[170:173], v[96:99]
	v_mfma_f32_16x16x32_bf16 v[88:91], v[230:233], v[170:173], v[88:91]
	v_mfma_f32_16x16x32_bf16 v[80:83], v[222:225], v[206:209], v[80:83]
	v_mfma_f32_16x16x32_bf16 v[72:75], v[230:233], v[206:209], v[72:75]
	v_mfma_f32_16x16x32_bf16 v[68:71], v[222:225], v[214:217], v[68:71]
	v_mfma_f32_16x16x32_bf16 v[64:67], v[230:233], v[214:217], v[64:67]
	s_setprio 0
	s_mov_b32 m0, s60
	v_lshl_add_u64 v[200:201], s[72:73], 0, v[132:133]
	s_barrier
	ds_read_b128 v[158:161], v145 offset:16384
	ds_read_b128 v[162:165], v145 offset:17408
	ds_read_b128 v[166:169], v145 offset:18432
	ds_read_b128 v[170:173], v145 offset:19456
	ds_read_b128 v[182:185], v145 offset:20480
	ds_read_b128 v[206:209], v145 offset:21504
	ds_read_b128 v[210:213], v145 offset:22528
	ds_read_b128 v[214:217], v145 offset:23552
	global_load_lds_dwordx4 v[200:201], off
	v_lshl_add_u64 v[202:203], s[72:73], 0, v[130:131]
	s_mov_b32 m0, s61
	s_nop 0
	global_load_lds_dwordx4 v[202:203], off
	s_barrier
	s_waitcnt lgkmcnt(0)
	s_setprio 1
	s_waitcnt lgkmcnt(0)
	v_mfma_f32_16x16x32_bf16 v[60:63], v[138:141], v[158:161], v[60:63]
	v_mfma_f32_16x16x32_bf16 v[56:59], v[150:153], v[158:161], v[56:59]
	v_mfma_f32_16x16x32_bf16 v[52:55], v[138:141], v[166:169], v[52:55]
	v_mfma_f32_16x16x32_bf16 v[44:47], v[150:153], v[166:169], v[44:47]
	v_mfma_f32_16x16x32_bf16 v[36:39], v[138:141], v[182:185], v[36:39]
	v_mfma_f32_16x16x32_bf16 v[28:31], v[150:153], v[182:185], v[28:31]
	v_mfma_f32_16x16x32_bf16 v[20:23], v[138:141], v[210:213], v[20:23]
	v_mfma_f32_16x16x32_bf16 v[12:15], v[150:153], v[210:213], v[12:15]
	v_mfma_f32_16x16x32_bf16 v[60:63], v[146:149], v[162:165], v[60:63]
	v_mfma_f32_16x16x32_bf16 v[56:59], v[154:157], v[162:165], v[56:59]
	v_mfma_f32_16x16x32_bf16 v[52:55], v[146:149], v[170:173], v[52:55]
	v_mfma_f32_16x16x32_bf16 v[44:47], v[154:157], v[170:173], v[44:47]
	v_mfma_f32_16x16x32_bf16 v[36:39], v[146:149], v[206:209], v[36:39]
	v_mfma_f32_16x16x32_bf16 v[28:31], v[154:157], v[206:209], v[28:31]
	v_mfma_f32_16x16x32_bf16 v[20:23], v[146:149], v[214:217], v[20:23]
	v_mfma_f32_16x16x32_bf16 v[12:15], v[154:157], v[214:217], v[12:15]
	s_setprio 0
	s_barrier
	s_add_u32 s2, s70, 0x80000
	s_addc_u32 s3, s71, 0
	s_add_i32 s1, s1, s53
	v_lshl_add_u64 v[138:139], s[2:3], 0, v[176:177]
	s_mov_b32 m0, s1
	s_nop 0
	global_load_lds_dwordx4 v[138:139], off
	v_lshl_add_u64 v[138:139], s[2:3], 0, v[128:129]
	s_add_i32 m0, s1, 0x2000
	s_nop 0
	global_load_lds_dwordx4 v[138:139], off
	s_waitcnt vmcnt(6)
	s_barrier
	s_setprio 1
	v_mfma_f32_16x16x32_bf16 v[48:51], v[218:221], v[158:161], v[48:51]
	v_mfma_f32_16x16x32_bf16 v[40:43], v[226:229], v[158:161], v[40:43]
	v_mfma_f32_16x16x32_bf16 v[32:35], v[218:221], v[166:169], v[32:35]
	v_mfma_f32_16x16x32_bf16 v[24:27], v[226:229], v[166:169], v[24:27]
	v_mfma_f32_16x16x32_bf16 v[16:19], v[218:221], v[182:185], v[16:19]
	v_mfma_f32_16x16x32_bf16 v[8:11], v[226:229], v[182:185], v[8:11]
	v_mfma_f32_16x16x32_bf16 v[4:7], v[218:221], v[210:213], v[4:7]
	v_mfma_f32_16x16x32_bf16 v[0:3], v[226:229], v[210:213], v[0:3]
	v_mfma_f32_16x16x32_bf16 v[48:51], v[222:225], v[162:165], v[48:51]
	v_mfma_f32_16x16x32_bf16 v[40:43], v[230:233], v[162:165], v[40:43]
	v_mfma_f32_16x16x32_bf16 v[32:35], v[222:225], v[170:173], v[32:35]
	v_mfma_f32_16x16x32_bf16 v[24:27], v[230:233], v[170:173], v[24:27]
	v_mfma_f32_16x16x32_bf16 v[16:19], v[222:225], v[206:209], v[16:19]
	v_mfma_f32_16x16x32_bf16 v[8:11], v[230:233], v[206:209], v[8:11]
	v_mfma_f32_16x16x32_bf16 v[4:7], v[222:225], v[214:217], v[4:7]
	v_mfma_f32_16x16x32_bf16 v[0:3], v[230:233], v[214:217], v[0:3]
	s_setprio 0
	s_add_i32 s1, 0, 0x18000
	v_add_u32_e32 v154, s1, v143
	s_barrier
	ds_read_b128 v[138:141], v154
	ds_read_b128 v[146:149], v154 offset:1024
	ds_read_b128 v[150:153], v154 offset:2048
	ds_read_b128 v[154:157], v154 offset:3072
	s_add_u32 s2, s72, 0x80000
	s_addc_u32 s3, s73, 0
	s_mov_b32 m0, s74
	v_lshl_add_u64 v[204:205], s[2:3], 0, v[132:133]
	ds_read_b128 v[158:161], v145 offset:32768
	ds_read_b128 v[162:165], v145 offset:33792
	ds_read_b128 v[166:169], v145 offset:34816
	ds_read_b128 v[170:173], v145 offset:35840
	ds_read_b128 v[182:185], v145 offset:36864
	ds_read_b128 v[206:209], v145 offset:37888
	ds_read_b128 v[210:213], v145 offset:38912
	ds_read_b128 v[214:217], v145 offset:39936
	global_load_lds_dwordx4 v[204:205], off
	v_lshl_add_u64 v[204:205], s[2:3], 0, v[130:131]
	s_mov_b32 m0, s75
	s_nop 0
	global_load_lds_dwordx4 v[204:205], off
	s_waitcnt lgkmcnt(8)
	s_barrier
	s_waitcnt lgkmcnt(0)
	s_setprio 1
	s_waitcnt lgkmcnt(0)
	v_mfma_f32_16x16x32_bf16 v[124:127], v[138:141], v[158:161], v[124:127]
	v_mfma_f32_16x16x32_bf16 v[120:123], v[150:153], v[158:161], v[120:123]
	v_mfma_f32_16x16x32_bf16 v[116:119], v[138:141], v[166:169], v[116:119]
	v_mfma_f32_16x16x32_bf16 v[108:111], v[150:153], v[166:169], v[108:111]
	v_mfma_f32_16x16x32_bf16 v[100:103], v[138:141], v[182:185], v[100:103]
	v_mfma_f32_16x16x32_bf16 v[92:95], v[150:153], v[182:185], v[92:95]
	v_mfma_f32_16x16x32_bf16 v[84:87], v[138:141], v[210:213], v[84:87]
	v_mfma_f32_16x16x32_bf16 v[76:79], v[150:153], v[210:213], v[76:79]
	v_mfma_f32_16x16x32_bf16 v[124:127], v[146:149], v[162:165], v[124:127]
	v_mfma_f32_16x16x32_bf16 v[120:123], v[154:157], v[162:165], v[120:123]
	v_mfma_f32_16x16x32_bf16 v[116:119], v[146:149], v[170:173], v[116:119]
	v_mfma_f32_16x16x32_bf16 v[108:111], v[154:157], v[170:173], v[108:111]
	v_mfma_f32_16x16x32_bf16 v[100:103], v[146:149], v[206:209], v[100:103]
	v_mfma_f32_16x16x32_bf16 v[92:95], v[154:157], v[206:209], v[92:95]
	v_mfma_f32_16x16x32_bf16 v[84:87], v[146:149], v[214:217], v[84:87]
	v_mfma_f32_16x16x32_bf16 v[76:79], v[154:157], v[214:217], v[76:79]
	s_setprio 0
	s_barrier
	s_add_i32 s12, 0, 0x1c000
	s_add_i32 s1, s1, s53
	v_add_u32_e32 v188, s12, v143
	v_lshl_add_u64 v[174:175], v[174:175], 0, s[20:21]
	s_mov_b32 m0, s1
	ds_read_b128 v[218:221], v188
	ds_read_b128 v[222:225], v188 offset:1024
	ds_read_b128 v[226:229], v188 offset:2048
	ds_read_b128 v[230:233], v188 offset:3072
	global_load_lds_dwordx4 v[174:175], off
	v_lshl_add_u64 v[174:175], v[186:187], 0, s[20:21]
	s_add_i32 m0, s1, 0x2000
	s_nop 0
	global_load_lds_dwordx4 v[174:175], off
	s_barrier
	s_waitcnt lgkmcnt(0)
	s_setprio 1
	s_waitcnt lgkmcnt(0)
	v_mfma_f32_16x16x32_bf16 v[112:115], v[218:221], v[158:161], v[112:115]
	v_mfma_f32_16x16x32_bf16 v[104:107], v[226:229], v[158:161], v[104:107]
	v_mfma_f32_16x16x32_bf16 v[96:99], v[218:221], v[166:169], v[96:99]
	v_mfma_f32_16x16x32_bf16 v[88:91], v[226:229], v[166:169], v[88:91]
	v_mfma_f32_16x16x32_bf16 v[80:83], v[218:221], v[182:185], v[80:83]
	v_mfma_f32_16x16x32_bf16 v[72:75], v[226:229], v[182:185], v[72:75]
	v_mfma_f32_16x16x32_bf16 v[68:71], v[218:221], v[210:213], v[68:71]
	v_mfma_f32_16x16x32_bf16 v[64:67], v[226:229], v[210:213], v[64:67]
	v_mfma_f32_16x16x32_bf16 v[112:115], v[222:225], v[162:165], v[112:115]
	v_mfma_f32_16x16x32_bf16 v[104:107], v[230:233], v[162:165], v[104:107]
	v_mfma_f32_16x16x32_bf16 v[96:99], v[222:225], v[170:173], v[96:99]
	v_mfma_f32_16x16x32_bf16 v[88:91], v[230:233], v[170:173], v[88:91]
	v_mfma_f32_16x16x32_bf16 v[80:83], v[222:225], v[206:209], v[80:83]
	v_mfma_f32_16x16x32_bf16 v[72:75], v[230:233], v[206:209], v[72:75]
	v_mfma_f32_16x16x32_bf16 v[68:71], v[222:225], v[214:217], v[68:71]
	v_mfma_f32_16x16x32_bf16 v[64:67], v[230:233], v[214:217], v[64:67]
	s_setprio 0
	s_mov_b32 m0, s76
	v_lshl_add_u64 v[174:175], v[200:201], 0, s[20:21]
	s_barrier
	ds_read_b128 v[158:161], v145 offset:49152
	ds_read_b128 v[162:165], v145 offset:50176
	ds_read_b128 v[166:169], v145 offset:51200
	ds_read_b128 v[170:173], v145 offset:52224
	ds_read_b128 v[182:185], v145 offset:53248
	ds_read_b128 v[206:209], v145 offset:54272
	ds_read_b128 v[210:213], v145 offset:55296
	ds_read_b128 v[214:217], v145 offset:56320
	global_load_lds_dwordx4 v[174:175], off
	v_lshl_add_u64 v[174:175], v[202:203], 0, s[20:21]
	s_mov_b32 m0, s77
	s_nop 0
	global_load_lds_dwordx4 v[174:175], off
	s_barrier
	s_waitcnt lgkmcnt(0)
	s_setprio 1
	s_waitcnt lgkmcnt(0)
	v_mfma_f32_16x16x32_bf16 v[60:63], v[138:141], v[158:161], v[60:63]
	v_mfma_f32_16x16x32_bf16 v[56:59], v[150:153], v[158:161], v[56:59]
	v_mfma_f32_16x16x32_bf16 v[52:55], v[138:141], v[166:169], v[52:55]
	v_mfma_f32_16x16x32_bf16 v[44:47], v[150:153], v[166:169], v[44:47]
	v_mfma_f32_16x16x32_bf16 v[36:39], v[138:141], v[182:185], v[36:39]
	v_mfma_f32_16x16x32_bf16 v[28:31], v[150:153], v[182:185], v[28:31]
	v_mfma_f32_16x16x32_bf16 v[20:23], v[138:141], v[210:213], v[20:23]
	v_mfma_f32_16x16x32_bf16 v[12:15], v[150:153], v[210:213], v[12:15]
	v_mfma_f32_16x16x32_bf16 v[60:63], v[146:149], v[162:165], v[60:63]
	v_mfma_f32_16x16x32_bf16 v[56:59], v[154:157], v[162:165], v[56:59]
	v_mfma_f32_16x16x32_bf16 v[52:55], v[146:149], v[170:173], v[52:55]
	v_mfma_f32_16x16x32_bf16 v[44:47], v[154:157], v[170:173], v[44:47]
	v_mfma_f32_16x16x32_bf16 v[36:39], v[146:149], v[206:209], v[36:39]
	v_mfma_f32_16x16x32_bf16 v[28:31], v[154:157], v[206:209], v[28:31]
	v_mfma_f32_16x16x32_bf16 v[20:23], v[146:149], v[214:217], v[20:23]
	v_mfma_f32_16x16x32_bf16 v[12:15], v[154:157], v[214:217], v[12:15]
	s_setprio 0
	s_barrier
	s_add_u32 s2, s70, 0x80080
	s_addc_u32 s3, s71, 0
	s_add_i32 s1, s12, s53
	v_lshl_add_u64 v[138:139], s[2:3], 0, v[176:177]
	s_mov_b32 m0, s1
	s_nop 0
	global_load_lds_dwordx4 v[138:139], off
	v_lshl_add_u64 v[138:139], s[2:3], 0, v[128:129]
	s_add_i32 m0, s1, 0x2000
	s_nop 0
	global_load_lds_dwordx4 v[138:139], off
	s_waitcnt vmcnt(6)
	s_barrier
	s_setprio 1
	v_mfma_f32_16x16x32_bf16 v[48:51], v[218:221], v[158:161], v[48:51]
	v_mfma_f32_16x16x32_bf16 v[40:43], v[226:229], v[158:161], v[40:43]
	v_mfma_f32_16x16x32_bf16 v[32:35], v[218:221], v[166:169], v[32:35]
	v_mfma_f32_16x16x32_bf16 v[24:27], v[226:229], v[166:169], v[24:27]
	v_mfma_f32_16x16x32_bf16 v[16:19], v[218:221], v[182:185], v[16:19]
	v_mfma_f32_16x16x32_bf16 v[8:11], v[226:229], v[182:185], v[8:11]
	v_mfma_f32_16x16x32_bf16 v[4:7], v[218:221], v[210:213], v[4:7]
	v_mfma_f32_16x16x32_bf16 v[0:3], v[226:229], v[210:213], v[0:3]
	v_mfma_f32_16x16x32_bf16 v[48:51], v[222:225], v[162:165], v[48:51]
	v_mfma_f32_16x16x32_bf16 v[40:43], v[230:233], v[162:165], v[40:43]
	v_mfma_f32_16x16x32_bf16 v[32:35], v[222:225], v[170:173], v[32:35]
	v_mfma_f32_16x16x32_bf16 v[24:27], v[230:233], v[170:173], v[24:27]
	v_mfma_f32_16x16x32_bf16 v[16:19], v[222:225], v[206:209], v[16:19]
	v_mfma_f32_16x16x32_bf16 v[8:11], v[230:233], v[206:209], v[8:11]
	v_mfma_f32_16x16x32_bf16 v[4:7], v[222:225], v[214:217], v[4:7]
	v_mfma_f32_16x16x32_bf16 v[0:3], v[230:233], v[214:217], v[0:3]
	s_setprio 0
	s_add_i32 s87, s87, 2
	s_add_u32 s68, s68, 0x100
	s_addc_u32 s69, s69, 0
	s_add_u32 s83, s83, 0x100
	s_addc_u32 s86, s86, 0
	s_cmp_gt_u32 s87, 29
	s_barrier
	s_cbranch_scc0 .LBB0_189
	s_cmp_eq_u32 s88, 0
	s_cbranch_scc1 .Lrs_skip
	s_add_i32 s98, s80, 1
	s_cmp_eq_u32 s89, s98
	s_cbranch_scc1 .Lrs_mul
	v_readlane_b32 s98, v255, 1
	v_readlane_b32 s99, v255, 2
	v_lshl_add_u32 v200, s80, 8, v142
	v_bfe_u32 v201, v144, 3, 2
	v_lshlrev_b32_e32 v201, 5, v201
	v_lshl_add_u32 v200, v200, 7, v201
	v_add_u32_e32 v201, 0x1000, v200
	v_add_u32_e32 v202, 0x4000, v200
	v_add_u32_e32 v203, 0x5000, v200
	v_mbcnt_lo_u32_b32 v204, -1, 0
	v_mbcnt_hi_u32_b32 v204, -1, v204
	v_xor_b32_e32 v205, 16, v204
	v_xor_b32_e32 v204, 32, v204
	v_lshlrev_b32_e32 v205, 2, v205
	v_lshlrev_b32_e32 v204, 2, v204
	global_load_dwordx4 v[208:211], v200, s[98:99]
	global_load_dwordx4 v[212:215], v200, s[98:99] offset:16
	global_load_dwordx4 v[216:219], v200, s[98:99] offset:2048
	global_load_dwordx4 v[220:223], v200, s[98:99] offset:2064
	global_load_dwordx4 v[224:227], v201, s[98:99]
	global_load_dwordx4 v[228:231], v201, s[98:99] offset:16
	global_load_dwordx4 v[232:235], v201, s[98:99] offset:2048
	global_load_dwordx4 v[236:239], v201, s[98:99] offset:2064
	s_waitcnt vmcnt(0)
	v_add_f32_e32 v208, v208, v209
	v_add_f32_e32 v210, v210, v211
	v_add_f32_e32 v212, v212, v213
	v_add_f32_e32 v214, v214, v215
	v_add_f32_e32 v208, v208, v210
	v_add_f32_e32 v212, v212, v214
	v_add_f32_e32 v190, v208, v212
	v_add_f32_e32 v216, v216, v217
	v_add_f32_e32 v218, v218, v219
	v_add_f32_e32 v220, v220, v221
	v_add_f32_e32 v222, v222, v223
	v_add_f32_e32 v216, v216, v218
	v_add_f32_e32 v220, v220, v222
	v_add_f32_e32 v191, v216, v220
	v_add_f32_e32 v224, v224, v225
	v_add_f32_e32 v226, v226, v227
	v_add_f32_e32 v228, v228, v229
	v_add_f32_e32 v230, v230, v231
	v_add_f32_e32 v224, v224, v226
	v_add_f32_e32 v228, v228, v230
	v_add_f32_e32 v192, v224, v228
	v_add_f32_e32 v232, v232, v233
	v_add_f32_e32 v234, v234, v235
	v_add_f32_e32 v236, v236, v237
	v_add_f32_e32 v238, v238, v239
	v_add_f32_e32 v232, v232, v234
	v_add_f32_e32 v236, v236, v238
	v_add_f32_e32 v194, v232, v236
	global_load_dwordx4 v[208:211], v202, s[98:99]
	global_load_dwordx4 v[212:215], v202, s[98:99] offset:16
	global_load_dwordx4 v[216:219], v202, s[98:99] offset:2048
	global_load_dwordx4 v[220:223], v202, s[98:99] offset:2064
	global_load_dwordx4 v[224:227], v203, s[98:99]
	global_load_dwordx4 v[228:231], v203, s[98:99] offset:16
	global_load_dwordx4 v[232:235], v203, s[98:99] offset:2048
	global_load_dwordx4 v[236:239], v203, s[98:99] offset:2064
	s_waitcnt vmcnt(0)
	v_add_f32_e32 v208, v208, v209
	v_add_f32_e32 v210, v210, v211
	v_add_f32_e32 v212, v212, v213
	v_add_f32_e32 v214, v214, v215
	v_add_f32_e32 v208, v208, v210
	v_add_f32_e32 v212, v212, v214
	v_add_f32_e32 v195, v208, v212
	v_add_f32_e32 v216, v216, v217
	v_add_f32_e32 v218, v218, v219
	v_add_f32_e32 v220, v220, v221
	v_add_f32_e32 v222, v222, v223
	v_add_f32_e32 v216, v216, v218
	v_add_f32_e32 v220, v220, v222
	v_add_f32_e32 v196, v216, v220
	v_add_f32_e32 v224, v224, v225
	v_add_f32_e32 v226, v226, v227
	v_add_f32_e32 v228, v228, v229
	v_add_f32_e32 v230, v230, v231
	v_add_f32_e32 v224, v224, v226
	v_add_f32_e32 v228, v228, v230
	v_add_f32_e32 v198, v224, v228
	v_add_f32_e32 v232, v232, v233
	v_add_f32_e32 v234, v234, v235
	v_add_f32_e32 v236, v236, v237
	v_add_f32_e32 v238, v238, v239
	v_add_f32_e32 v232, v232, v234
	v_add_f32_e32 v236, v236, v238
	v_add_f32_e32 v248, v232, v236
	ds_bpermute_b32 v240, v205, v190
	ds_bpermute_b32 v241, v205, v191
	ds_bpermute_b32 v242, v205, v192
	ds_bpermute_b32 v243, v205, v194
	ds_bpermute_b32 v244, v205, v195
	ds_bpermute_b32 v245, v205, v196
	ds_bpermute_b32 v246, v205, v198
	ds_bpermute_b32 v247, v205, v248
	s_waitcnt lgkmcnt(0)
	v_add_f32_e32 v190, v190, v240
	v_add_f32_e32 v191, v191, v241
	v_add_f32_e32 v192, v192, v242
	v_add_f32_e32 v194, v194, v243
	v_add_f32_e32 v195, v195, v244
	v_add_f32_e32 v196, v196, v245
	v_add_f32_e32 v198, v198, v246
	v_add_f32_e32 v248, v248, v247
	ds_bpermute_b32 v240, v204, v190
	ds_bpermute_b32 v241, v204, v191
	ds_bpermute_b32 v242, v204, v192
	ds_bpermute_b32 v243, v204, v194
	ds_bpermute_b32 v244, v204, v195
	ds_bpermute_b32 v245, v204, v196
	ds_bpermute_b32 v246, v204, v198
	ds_bpermute_b32 v247, v204, v248
	s_waitcnt lgkmcnt(0)
	v_add_f32_e32 v190, v190, v240
	v_add_f32_e32 v191, v191, v241
	v_add_f32_e32 v192, v192, v242
	v_add_f32_e32 v194, v194, v243
	v_add_f32_e32 v195, v195, v244
	v_add_f32_e32 v196, v196, v245
	v_add_f32_e32 v198, v198, v246
	v_add_f32_e32 v248, v248, v247
	v_mul_f32_e32 v190, 0x3a000000, v190
	v_add_f32_e32 v190, 0x358637bd, v190
	v_mul_f32_e32 v191, 0x3a000000, v191
	v_add_f32_e32 v191, 0x358637bd, v191
	v_mul_f32_e32 v192, 0x3a000000, v192
	v_add_f32_e32 v192, 0x358637bd, v192
	v_mul_f32_e32 v194, 0x3a000000, v194
	v_add_f32_e32 v194, 0x358637bd, v194
	v_mul_f32_e32 v195, 0x3a000000, v195
	v_add_f32_e32 v195, 0x358637bd, v195
	v_mul_f32_e32 v196, 0x3a000000, v196
	v_add_f32_e32 v196, 0x358637bd, v196
	v_mul_f32_e32 v198, 0x3a000000, v198
	v_add_f32_e32 v198, 0x358637bd, v198
	v_mul_f32_e32 v248, 0x3a000000, v248
	v_add_f32_e32 v248, 0x358637bd, v248
	v_rsq_f32_e32 v190, v190
	v_rsq_f32_e32 v191, v191
	v_rsq_f32_e32 v192, v192
	v_rsq_f32_e32 v194, v194
	v_rsq_f32_e32 v195, v195
	v_rsq_f32_e32 v196, v196
	v_rsq_f32_e32 v198, v198
	v_rsq_f32_e32 v248, v248
	s_add_i32 s89, s80, 1
